# v17 plus: chunk-local triangular solve moved to the f32 matrix cores (v_mfma_f32_16x16x4_f32): diagonal 16x16 blocks inverted by substitution into an LDS table, off-diagonal updates and block solves a
# speedup vs baseline: 1.0289x; 1.0070x over previous
.LBB0_628:
	s_or_b64 exec, exec, s[2:3]
	s_movk_i32 s2, 0x80
	v_cmp_gt_i32_e64 s[4:5], s2, v16
	s_waitcnt lgkmcnt(0)
	s_barrier
	s_mov_b64 s[6:7], exec
	v_readfirstlane_b32 s2, v160
	v_and_b32_e32 v20, 15, v160
	v_bfe_u32 v21, v160, 4, 2
	s_lshr_b32 s2, s2, 6
	s_and_b32 s4, s2, 3
	s_lshl_b32 s4, s4, 6
	s_cmp_lt_u32 s2, 4
	s_mov_b32 s5, 0x4100
	s_cselect_b32 s5, 0x8200, s5
	s_mov_b32 s2, 0x10900
	s_cselect_b32 s2, 0x10800, s2
	s_add_u32 s4, s4, s5
	v_lshl_add_u32 v8, v20, 2, v195
	v_add_u32_e32 v8, s4, v8
	v_mul_u32_u24_e32 v23, 0x410, v21
	v_add_u32_e32 v9, v8, v23
	v_mul_u32_u24_e32 v23, 0x104, v21
	v_add_u32_e32 v10, v8, v23
	v_lshl_add_u32 v11, v21, 4, v195
	v_add_u32_e32 v11, s2, v11
	v_mul_u32_u24_e32 v23, 0x110, v20
	v_lshl_add_u32 v23, v21, 2, v23
	s_mov_b32 s5, 0xc300
	v_add3_u32 v12, v195, v23, s5
	v_lshlrev_b32_e32 v23, 6, v20
	v_lshl_add_u32 v23, v21, 2, v23
	s_mov_b32 s4, 0x1e200
	v_add3_u32 v13, v195, v23, s4
	v_lshlrev_b32_e32 v23, 10, v21
	v_lshl_add_u32 v23, v20, 2, v23
	v_add3_u32 v14, v195, v23, s4
	v_mul_u32_u24_e32 v23, 0x1140, v21
	v_add3_u32 v15, v195, v23, s5
	v_cvt_f32_u32_e32 v22, v20
	ds_read_b128 v[214:217], v15 offset:272
	ds_read_b128 v[230:233], v15 offset:544
	v_sub_f32_e32 v23, 0, v22
	v_min_f32_e64 v23, |v23|, 1.0
	v_sub_f32_e32 v64, 1.0, v23
	v_sub_f32_e32 v23, 1.0, v22
	v_min_f32_e64 v23, |v23|, 1.0
	v_sub_f32_e32 v65, 1.0, v23
	ds_read_b128 v[198:201], v15 offset:816
	s_waitcnt lgkmcnt(2)
	v_fma_f32 v65, -v214, v64, v65
	v_sub_f32_e32 v23, 2.0, v22
	v_min_f32_e64 v23, |v23|, 1.0
	v_sub_f32_e32 v66, 1.0, v23
	ds_read_b128 v[214:217], v15 offset:1088
	s_waitcnt lgkmcnt(2)
	v_fma_f32 v66, -v230, v64, v66
	v_fma_f32 v66, -v231, v65, v66
	v_sub_f32_e32 v23, 0x40400000, v22
	v_min_f32_e64 v23, |v23|, 1.0
	v_sub_f32_e32 v67, 1.0, v23
	ds_read_b128 v[230:233], v15 offset:1360
	ds_read_b128 v[234:237], v15 offset:1376
	s_waitcnt lgkmcnt(3)
	v_fma_f32 v67, -v198, v64, v67
	v_fma_f32 v67, -v199, v65, v67
	v_fma_f32 v67, -v200, v66, v67
	v_sub_f32_e32 v23, 4.0, v22
	v_min_f32_e64 v23, |v23|, 1.0
	v_sub_f32_e32 v68, 1.0, v23
	ds_read_b128 v[198:201], v15 offset:1632
	ds_read_b128 v[202:205], v15 offset:1648
	s_waitcnt lgkmcnt(4)
	v_fma_f32 v68, -v214, v64, v68
	v_fma_f32 v68, -v215, v65, v68
	v_fma_f32 v68, -v216, v66, v68
	v_fma_f32 v68, -v217, v67, v68
	v_sub_f32_e32 v23, 0x40a00000, v22
	v_min_f32_e64 v23, |v23|, 1.0
	v_sub_f32_e32 v69, 1.0, v23
	ds_read_b128 v[214:217], v15 offset:1904
	ds_read_b128 v[218:221], v15 offset:1920
	s_waitcnt lgkmcnt(5)
	v_fma_f32 v69, -v230, v64, v69
	v_fma_f32 v69, -v231, v65, v69
	v_fma_f32 v69, -v232, v66, v69
	v_fma_f32 v69, -v233, v67, v69
	s_waitcnt lgkmcnt(4)
	v_fma_f32 v69, -v234, v68, v69
	v_sub_f32_e32 v23, 0x40c00000, v22
	v_min_f32_e64 v23, |v23|, 1.0
	v_sub_f32_e32 v70, 1.0, v23
	ds_read_b128 v[230:233], v15 offset:2176
	ds_read_b128 v[234:237], v15 offset:2192
	s_waitcnt lgkmcnt(5)
	v_fma_f32 v70, -v198, v64, v70
	v_fma_f32 v70, -v199, v65, v70
	v_fma_f32 v70, -v200, v66, v70
	v_fma_f32 v70, -v201, v67, v70
	s_waitcnt lgkmcnt(4)
	v_fma_f32 v70, -v202, v68, v70
	v_fma_f32 v70, -v203, v69, v70
	v_sub_f32_e32 v23, 0x40e00000, v22
	v_min_f32_e64 v23, |v23|, 1.0
	v_sub_f32_e32 v71, 1.0, v23
	ds_read_b128 v[198:201], v15 offset:2448
	ds_read_b128 v[202:205], v15 offset:2464
	ds_read_b128 v[206:209], v15 offset:2480
	s_waitcnt lgkmcnt(6)
	v_fma_f32 v71, -v214, v64, v71
	v_fma_f32 v71, -v215, v65, v71
	v_fma_f32 v71, -v216, v66, v71
	v_fma_f32 v71, -v217, v67, v71
	s_waitcnt lgkmcnt(5)
	v_fma_f32 v71, -v218, v68, v71
	v_fma_f32 v71, -v219, v69, v71
	v_fma_f32 v71, -v220, v70, v71
	v_sub_f32_e32 v23, 0x41000000, v22
	v_min_f32_e64 v23, |v23|, 1.0
	v_sub_f32_e32 v72, 1.0, v23
	ds_read_b128 v[214:217], v15 offset:2720
	ds_read_b128 v[218:221], v15 offset:2736
	ds_read_b128 v[222:225], v15 offset:2752
	s_waitcnt lgkmcnt(7)
	v_fma_f32 v72, -v230, v64, v72
	v_fma_f32 v72, -v231, v65, v72
	v_fma_f32 v72, -v232, v66, v72
	v_fma_f32 v72, -v233, v67, v72
	s_waitcnt lgkmcnt(6)
	v_fma_f32 v72, -v234, v68, v72
	v_fma_f32 v72, -v235, v69, v72
	v_fma_f32 v72, -v236, v70, v72
	v_fma_f32 v72, -v237, v71, v72
	v_sub_f32_e32 v23, 0x41100000, v22
	v_min_f32_e64 v23, |v23|, 1.0
	v_sub_f32_e32 v73, 1.0, v23
	ds_read_b128 v[230:233], v15 offset:2992
	ds_read_b128 v[234:237], v15 offset:3008
	ds_read_b128 v[156:159], v15 offset:3024
	s_waitcnt lgkmcnt(8)
	v_fma_f32 v73, -v198, v64, v73
	v_fma_f32 v73, -v199, v65, v73
	v_fma_f32 v73, -v200, v66, v73
	v_fma_f32 v73, -v201, v67, v73
	s_waitcnt lgkmcnt(7)
	v_fma_f32 v73, -v202, v68, v73
	v_fma_f32 v73, -v203, v69, v73
	v_fma_f32 v73, -v204, v70, v73
	v_fma_f32 v73, -v205, v71, v73
	s_waitcnt lgkmcnt(6)
	v_fma_f32 v73, -v206, v72, v73
	v_sub_f32_e32 v23, 0x41200000, v22
	v_min_f32_e64 v23, |v23|, 1.0
	v_sub_f32_e32 v74, 1.0, v23
	ds_read_b128 v[198:201], v15 offset:3264
	ds_read_b128 v[202:205], v15 offset:3280
	ds_read_b128 v[206:209], v15 offset:3296
	s_waitcnt lgkmcnt(8)
	v_fma_f32 v74, -v214, v64, v74
	v_fma_f32 v74, -v215, v65, v74
	v_fma_f32 v74, -v216, v66, v74
	v_fma_f32 v74, -v217, v67, v74
	s_waitcnt lgkmcnt(7)
	v_fma_f32 v74, -v218, v68, v74
	v_fma_f32 v74, -v219, v69, v74
	v_fma_f32 v74, -v220, v70, v74
	v_fma_f32 v74, -v221, v71, v74
	s_waitcnt lgkmcnt(6)
	v_fma_f32 v74, -v222, v72, v74
	v_fma_f32 v74, -v223, v73, v74
	v_sub_f32_e32 v23, 0x41300000, v22
	v_min_f32_e64 v23, |v23|, 1.0
	v_sub_f32_e32 v75, 1.0, v23
	ds_read_b128 v[214:217], v15 offset:3536
	ds_read_b128 v[218:221], v15 offset:3552
	ds_read_b128 v[222:225], v15 offset:3568
	ds_read_b128 v[226:229], v15 offset:3584
	s_waitcnt lgkmcnt(9)
	v_fma_f32 v75, -v230, v64, v75
	v_fma_f32 v75, -v231, v65, v75
	v_fma_f32 v75, -v232, v66, v75
	v_fma_f32 v75, -v233, v67, v75
	s_waitcnt lgkmcnt(8)
	v_fma_f32 v75, -v234, v68, v75
	v_fma_f32 v75, -v235, v69, v75
	v_fma_f32 v75, -v236, v70, v75
	v_fma_f32 v75, -v237, v71, v75
	s_waitcnt lgkmcnt(7)
	v_fma_f32 v75, -v156, v72, v75
	v_fma_f32 v75, -v157, v73, v75
	v_fma_f32 v75, -v158, v74, v75
	v_sub_f32_e32 v23, 0x41400000, v22
	v_min_f32_e64 v23, |v23|, 1.0
	v_sub_f32_e32 v76, 1.0, v23
	ds_read_b128 v[230:233], v15 offset:3808
	ds_read_b128 v[234:237], v15 offset:3824
	ds_read_b128 v[156:159], v15 offset:3840
	ds_read_b128 v[164:167], v15 offset:3856
	s_waitcnt lgkmcnt(10)
	v_fma_f32 v76, -v198, v64, v76
	v_fma_f32 v76, -v199, v65, v76
	v_fma_f32 v76, -v200, v66, v76
	v_fma_f32 v76, -v201, v67, v76
	s_waitcnt lgkmcnt(9)
	v_fma_f32 v76, -v202, v68, v76
	v_fma_f32 v76, -v203, v69, v76
	v_fma_f32 v76, -v204, v70, v76
	v_fma_f32 v76, -v205, v71, v76
	s_waitcnt lgkmcnt(8)
	v_fma_f32 v76, -v206, v72, v76
	v_fma_f32 v76, -v207, v73, v76
	v_fma_f32 v76, -v208, v74, v76
	v_fma_f32 v76, -v209, v75, v76
	v_sub_f32_e32 v23, 0x41500000, v22
	v_min_f32_e64 v23, |v23|, 1.0
	v_sub_f32_e32 v77, 1.0, v23
	ds_read_b128 v[198:201], v15 offset:4080
	ds_read_b128 v[202:205], v15 offset:4096
	ds_read_b128 v[206:209], v15 offset:4112
	ds_read_b128 v[210:213], v15 offset:4128
	s_waitcnt lgkmcnt(11)
	v_fma_f32 v77, -v214, v64, v77
	v_fma_f32 v77, -v215, v65, v77
	v_fma_f32 v77, -v216, v66, v77
	v_fma_f32 v77, -v217, v67, v77
	s_waitcnt lgkmcnt(10)
	v_fma_f32 v77, -v218, v68, v77
	v_fma_f32 v77, -v219, v69, v77
	v_fma_f32 v77, -v220, v70, v77
	v_fma_f32 v77, -v221, v71, v77
	s_waitcnt lgkmcnt(9)
	v_fma_f32 v77, -v222, v72, v77
	v_fma_f32 v77, -v223, v73, v77
	v_fma_f32 v77, -v224, v74, v77
	v_fma_f32 v77, -v225, v75, v77
	s_waitcnt lgkmcnt(8)
	v_fma_f32 v77, -v226, v76, v77
	v_sub_f32_e32 v23, 0x41600000, v22
	v_min_f32_e64 v23, |v23|, 1.0
	v_sub_f32_e32 v78, 1.0, v23
	s_waitcnt lgkmcnt(7)
	v_fma_f32 v78, -v230, v64, v78
	v_fma_f32 v78, -v231, v65, v78
	v_fma_f32 v78, -v232, v66, v78
	v_fma_f32 v78, -v233, v67, v78
	s_waitcnt lgkmcnt(6)
	v_fma_f32 v78, -v234, v68, v78
	v_fma_f32 v78, -v235, v69, v78
	v_fma_f32 v78, -v236, v70, v78
	v_fma_f32 v78, -v237, v71, v78
	s_waitcnt lgkmcnt(5)
	v_fma_f32 v78, -v156, v72, v78
	v_fma_f32 v78, -v157, v73, v78
	v_fma_f32 v78, -v158, v74, v78
	v_fma_f32 v78, -v159, v75, v78
	s_waitcnt lgkmcnt(4)
	v_fma_f32 v78, -v164, v76, v78
	v_fma_f32 v78, -v165, v77, v78
	v_sub_f32_e32 v23, 0x41700000, v22
	v_min_f32_e64 v23, |v23|, 1.0
	v_sub_f32_e32 v79, 1.0, v23
	s_waitcnt lgkmcnt(3)
	v_fma_f32 v79, -v198, v64, v79
	v_fma_f32 v79, -v199, v65, v79
	v_fma_f32 v79, -v200, v66, v79
	v_fma_f32 v79, -v201, v67, v79
	s_waitcnt lgkmcnt(2)
	v_fma_f32 v79, -v202, v68, v79
	v_fma_f32 v79, -v203, v69, v79
	v_fma_f32 v79, -v204, v70, v79
	v_fma_f32 v79, -v205, v71, v79
	s_waitcnt lgkmcnt(1)
	v_fma_f32 v79, -v206, v72, v79
	v_fma_f32 v79, -v207, v73, v79
	v_fma_f32 v79, -v208, v74, v79
	v_fma_f32 v79, -v209, v75, v79
	s_waitcnt lgkmcnt(0)
	v_fma_f32 v79, -v210, v76, v79
	v_fma_f32 v79, -v211, v77, v79
	v_fma_f32 v79, -v212, v78, v79
	ds_write_b32 v14, v64 offset:0
	ds_write_b32 v14, v65 offset:64
	ds_write_b32 v14, v66 offset:128
	ds_write_b32 v14, v67 offset:192
	ds_write_b32 v14, v68 offset:256
	ds_write_b32 v14, v69 offset:320
	ds_write_b32 v14, v70 offset:384
	ds_write_b32 v14, v71 offset:448
	ds_write_b32 v14, v72 offset:512
	ds_write_b32 v14, v73 offset:576
	ds_write_b32 v14, v74 offset:640
	ds_write_b32 v14, v75 offset:704
	ds_write_b32 v14, v76 offset:768
	ds_write_b32 v14, v77 offset:832
	ds_write_b32 v14, v78 offset:896
	s_waitcnt lgkmcnt(14)
	ds_write_b32 v14, v79 offset:960
	s_waitcnt lgkmcnt(14)
	ds_read_b32 v112, v9 offset:0
	s_waitcnt lgkmcnt(14)
	ds_read_b32 v113, v9 offset:260
	s_waitcnt lgkmcnt(14)
	ds_read_b32 v114, v9 offset:520
	s_waitcnt lgkmcnt(14)
	ds_read_b32 v115, v9 offset:780
	s_waitcnt lgkmcnt(14)
	ds_read_b32 v116, v11 offset:0
	s_waitcnt lgkmcnt(14)
	ds_read_b32 v117, v11 offset:4
	s_waitcnt lgkmcnt(14)
	ds_read_b32 v118, v11 offset:8
	s_waitcnt lgkmcnt(14)
	ds_read_b32 v119, v11 offset:12
	s_waitcnt lgkmcnt(14)
	ds_read_b32 v108, v13 offset:0
	s_waitcnt lgkmcnt(14)
	ds_read_b32 v109, v13 offset:16
	s_waitcnt lgkmcnt(14)
	ds_read_b32 v110, v13 offset:32
	s_waitcnt lgkmcnt(14)
	ds_read_b32 v111, v13 offset:48
	s_waitcnt lgkmcnt(11)
	s_waitcnt lgkmcnt(7)
	v_mul_f32_e32 v32, v112, v116
	s_waitcnt lgkmcnt(6)
	v_mul_f32_e32 v33, v113, v117
	s_waitcnt lgkmcnt(5)
	v_mul_f32_e32 v34, v114, v118
	s_waitcnt lgkmcnt(4)
	v_mul_f32_e32 v35, v115, v119
	ds_write_b32 v9, v32 offset:0
	ds_write_b32 v9, v33 offset:260
	ds_write_b32 v9, v34 offset:520
	ds_write_b32 v9, v35 offset:780
	ds_read_b32 v40, v10 offset:0
	ds_read_b32 v41, v10 offset:1040
	ds_read_b32 v42, v10 offset:2080
	ds_read_b32 v43, v10 offset:3120
	s_waitcnt lgkmcnt(11)
	s_waitcnt lgkmcnt(3)
	v_mfma_f32_16x16x4_f32 v[44:47], v108, v40, 0
	s_waitcnt lgkmcnt(2)
	v_mfma_f32_16x16x4_f32 v[44:47], v109, v41, v[44:47]
	s_waitcnt lgkmcnt(1)
	v_mfma_f32_16x16x4_f32 v[44:47], v110, v42, v[44:47]
	s_waitcnt lgkmcnt(0)
	v_mfma_f32_16x16x4_f32 v[44:47], v111, v43, v[44:47]
	s_nop 9
	ds_write_b32 v9, v44 offset:0
	ds_write_b32 v9, v45 offset:260
	ds_write_b32 v9, v46 offset:520
	ds_write_b32 v9, v47 offset:780
	ds_read_b32 v80, v10 offset:0
	ds_read_b32 v81, v10 offset:1040
	ds_read_b32 v82, v10 offset:2080
	ds_read_b32 v83, v10 offset:3120
	ds_read_b32 v112, v9 offset:4160
	ds_read_b32 v113, v9 offset:4420
	ds_read_b32 v114, v9 offset:4680
	ds_read_b32 v115, v9 offset:4940
	ds_read_b32 v116, v11 offset:64
	ds_read_b32 v117, v11 offset:68
	ds_read_b32 v118, v11 offset:72
	s_waitcnt lgkmcnt(14)
	ds_read_b32 v119, v11 offset:76
	s_waitcnt lgkmcnt(14)
	ds_read_b32 v96, v12 offset:4352
	s_waitcnt lgkmcnt(14)
	ds_read_b32 v97, v12 offset:4368
	s_waitcnt lgkmcnt(14)
	ds_read_b32 v98, v12 offset:4384
	s_waitcnt lgkmcnt(14)
	ds_read_b32 v99, v12 offset:4400
	s_waitcnt lgkmcnt(14)
	ds_read_b32 v108, v13 offset:1024
	s_waitcnt lgkmcnt(14)
	ds_read_b32 v109, v13 offset:1040
	s_waitcnt lgkmcnt(14)
	ds_read_b32 v110, v13 offset:1056
	s_waitcnt lgkmcnt(14)
	ds_read_b32 v111, v13 offset:1072
	s_waitcnt lgkmcnt(11)
	v_mul_f32_e32 v32, v112, v116
	s_waitcnt lgkmcnt(10)
	v_mul_f32_e32 v33, v113, v117
	s_waitcnt lgkmcnt(9)
	v_mul_f32_e32 v34, v114, v118
	s_waitcnt lgkmcnt(8)
	v_mul_f32_e32 v35, v115, v119
	s_waitcnt lgkmcnt(7)
	v_mfma_f32_16x16x4_f32 v[28:31], v96, v80, 0
	s_waitcnt lgkmcnt(6)
	v_mfma_f32_16x16x4_f32 v[28:31], v97, v81, v[28:31]
	s_waitcnt lgkmcnt(5)
	v_mfma_f32_16x16x4_f32 v[28:31], v98, v82, v[28:31]
	s_waitcnt lgkmcnt(4)
	v_mfma_f32_16x16x4_f32 v[28:31], v99, v83, v[28:31]
	s_nop 9
	v_sub_f32_e32 v36, v32, v28
	v_sub_f32_e32 v37, v33, v29
	v_sub_f32_e32 v38, v34, v30
	v_sub_f32_e32 v39, v35, v31
	ds_write_b32 v9, v36 offset:4160
	ds_write_b32 v9, v37 offset:4420
	ds_write_b32 v9, v38 offset:4680
	ds_write_b32 v9, v39 offset:4940
	ds_read_b32 v40, v10 offset:4160
	ds_read_b32 v41, v10 offset:5200
	ds_read_b32 v42, v10 offset:6240
	ds_read_b32 v43, v10 offset:7280
	s_waitcnt lgkmcnt(11)
	s_waitcnt lgkmcnt(3)
	v_mfma_f32_16x16x4_f32 v[44:47], v108, v40, 0
	s_waitcnt lgkmcnt(2)
	v_mfma_f32_16x16x4_f32 v[44:47], v109, v41, v[44:47]
	s_waitcnt lgkmcnt(1)
	v_mfma_f32_16x16x4_f32 v[44:47], v110, v42, v[44:47]
	s_waitcnt lgkmcnt(0)
	v_mfma_f32_16x16x4_f32 v[44:47], v111, v43, v[44:47]
	s_nop 9
	ds_write_b32 v9, v44 offset:4160
	ds_write_b32 v9, v45 offset:4420
	ds_write_b32 v9, v46 offset:4680
	ds_write_b32 v9, v47 offset:4940
	ds_read_b32 v84, v10 offset:4160
	ds_read_b32 v85, v10 offset:5200
	ds_read_b32 v86, v10 offset:6240
	ds_read_b32 v87, v10 offset:7280
	ds_read_b32 v112, v9 offset:8320
	ds_read_b32 v113, v9 offset:8580
	ds_read_b32 v114, v9 offset:8840
	ds_read_b32 v115, v9 offset:9100
	ds_read_b32 v116, v11 offset:128
	ds_read_b32 v117, v11 offset:132
	ds_read_b32 v118, v11 offset:136
	s_waitcnt lgkmcnt(14)
	ds_read_b32 v119, v11 offset:140
	s_waitcnt lgkmcnt(14)
	ds_read_b32 v96, v12 offset:8704
	s_waitcnt lgkmcnt(14)
	ds_read_b32 v97, v12 offset:8720
	s_waitcnt lgkmcnt(14)
	ds_read_b32 v98, v12 offset:8736
	s_waitcnt lgkmcnt(14)
	ds_read_b32 v99, v12 offset:8752
	s_waitcnt lgkmcnt(14)
	ds_read_b32 v100, v12 offset:8768
	s_waitcnt lgkmcnt(14)
	ds_read_b32 v101, v12 offset:8784
	s_waitcnt lgkmcnt(14)
	ds_read_b32 v102, v12 offset:8800
	s_waitcnt lgkmcnt(14)
	ds_read_b32 v103, v12 offset:8816
	s_waitcnt lgkmcnt(14)
	ds_read_b32 v108, v13 offset:2048
	s_waitcnt lgkmcnt(14)
	ds_read_b32 v109, v13 offset:2064
	s_waitcnt lgkmcnt(14)
	ds_read_b32 v110, v13 offset:2080
	s_waitcnt lgkmcnt(14)
	ds_read_b32 v111, v13 offset:2096
	v_mul_f32_e32 v32, v112, v116
	s_waitcnt lgkmcnt(14)
	v_mul_f32_e32 v33, v113, v117
	s_waitcnt lgkmcnt(13)
	v_mul_f32_e32 v34, v114, v118
	s_waitcnt lgkmcnt(12)
	v_mul_f32_e32 v35, v115, v119
	s_waitcnt lgkmcnt(11)
	v_mfma_f32_16x16x4_f32 v[28:31], v96, v80, 0
	s_waitcnt lgkmcnt(10)
	v_mfma_f32_16x16x4_f32 v[28:31], v97, v81, v[28:31]
	s_waitcnt lgkmcnt(9)
	v_mfma_f32_16x16x4_f32 v[28:31], v98, v82, v[28:31]
	s_waitcnt lgkmcnt(8)
	v_mfma_f32_16x16x4_f32 v[28:31], v99, v83, v[28:31]
	s_waitcnt lgkmcnt(7)
	v_mfma_f32_16x16x4_f32 v[28:31], v100, v84, v[28:31]
	s_waitcnt lgkmcnt(6)
	v_mfma_f32_16x16x4_f32 v[28:31], v101, v85, v[28:31]
	s_waitcnt lgkmcnt(5)
	v_mfma_f32_16x16x4_f32 v[28:31], v102, v86, v[28:31]
	s_waitcnt lgkmcnt(4)
	v_mfma_f32_16x16x4_f32 v[28:31], v103, v87, v[28:31]
	s_nop 9
	v_sub_f32_e32 v36, v32, v28
	v_sub_f32_e32 v37, v33, v29
	v_sub_f32_e32 v38, v34, v30
	v_sub_f32_e32 v39, v35, v31
	ds_write_b32 v9, v36 offset:8320
	ds_write_b32 v9, v37 offset:8580
	ds_write_b32 v9, v38 offset:8840
	ds_write_b32 v9, v39 offset:9100
	ds_read_b32 v40, v10 offset:8320
	ds_read_b32 v41, v10 offset:9360
	ds_read_b32 v42, v10 offset:10400
	ds_read_b32 v43, v10 offset:11440
	s_waitcnt lgkmcnt(11)
	s_waitcnt lgkmcnt(3)
	v_mfma_f32_16x16x4_f32 v[44:47], v108, v40, 0
	s_waitcnt lgkmcnt(2)
	v_mfma_f32_16x16x4_f32 v[44:47], v109, v41, v[44:47]
	s_waitcnt lgkmcnt(1)
	v_mfma_f32_16x16x4_f32 v[44:47], v110, v42, v[44:47]
	s_waitcnt lgkmcnt(0)
	v_mfma_f32_16x16x4_f32 v[44:47], v111, v43, v[44:47]
	s_nop 9
	ds_write_b32 v9, v44 offset:8320
	ds_write_b32 v9, v45 offset:8580
	ds_write_b32 v9, v46 offset:8840
	ds_write_b32 v9, v47 offset:9100
	ds_read_b32 v88, v10 offset:8320
	ds_read_b32 v89, v10 offset:9360
	ds_read_b32 v90, v10 offset:10400
	ds_read_b32 v91, v10 offset:11440
	ds_read_b32 v112, v9 offset:12480
	ds_read_b32 v113, v9 offset:12740
	ds_read_b32 v114, v9 offset:13000
	ds_read_b32 v115, v9 offset:13260
	ds_read_b32 v116, v11 offset:192
	ds_read_b32 v117, v11 offset:196
	ds_read_b32 v118, v11 offset:200
	s_waitcnt lgkmcnt(14)
	ds_read_b32 v119, v11 offset:204
	s_waitcnt lgkmcnt(14)
	ds_read_b32 v96, v12 offset:13056
	s_waitcnt lgkmcnt(14)
	ds_read_b32 v97, v12 offset:13072
	s_waitcnt lgkmcnt(14)
	ds_read_b32 v98, v12 offset:13088
	s_waitcnt lgkmcnt(14)
	ds_read_b32 v99, v12 offset:13104
	s_waitcnt lgkmcnt(14)
	ds_read_b32 v100, v12 offset:13120
	s_waitcnt lgkmcnt(14)
	ds_read_b32 v101, v12 offset:13136
	s_waitcnt lgkmcnt(14)
	ds_read_b32 v102, v12 offset:13152
	s_waitcnt lgkmcnt(14)
	ds_read_b32 v103, v12 offset:13168
	s_waitcnt lgkmcnt(14)
	ds_read_b32 v104, v12 offset:13184
	s_waitcnt lgkmcnt(14)
	ds_read_b32 v105, v12 offset:13200
	s_waitcnt lgkmcnt(14)
	ds_read_b32 v106, v12 offset:13216
	s_waitcnt lgkmcnt(14)
	ds_read_b32 v107, v12 offset:13232
	s_waitcnt lgkmcnt(14)
	ds_read_b32 v108, v13 offset:3072
	s_waitcnt lgkmcnt(14)
	ds_read_b32 v109, v13 offset:3088
	s_waitcnt lgkmcnt(14)
	ds_read_b32 v110, v13 offset:3104
	s_waitcnt lgkmcnt(14)
	ds_read_b32 v111, v13 offset:3120
	v_mul_f32_e32 v32, v112, v116
	v_mul_f32_e32 v33, v113, v117
	v_mul_f32_e32 v34, v114, v118
	v_mul_f32_e32 v35, v115, v119
	v_mfma_f32_16x16x4_f32 v[28:31], v96, v80, 0
	s_waitcnt lgkmcnt(14)
	v_mfma_f32_16x16x4_f32 v[28:31], v97, v81, v[28:31]
	s_waitcnt lgkmcnt(13)
	v_mfma_f32_16x16x4_f32 v[28:31], v98, v82, v[28:31]
	s_waitcnt lgkmcnt(12)
	v_mfma_f32_16x16x4_f32 v[28:31], v99, v83, v[28:31]
	s_waitcnt lgkmcnt(11)
	v_mfma_f32_16x16x4_f32 v[28:31], v100, v84, v[28:31]
	s_waitcnt lgkmcnt(10)
	v_mfma_f32_16x16x4_f32 v[28:31], v101, v85, v[28:31]
	s_waitcnt lgkmcnt(9)
	v_mfma_f32_16x16x4_f32 v[28:31], v102, v86, v[28:31]
	s_waitcnt lgkmcnt(8)
	v_mfma_f32_16x16x4_f32 v[28:31], v103, v87, v[28:31]
	s_waitcnt lgkmcnt(7)
	v_mfma_f32_16x16x4_f32 v[28:31], v104, v88, v[28:31]
	s_waitcnt lgkmcnt(6)
	v_mfma_f32_16x16x4_f32 v[28:31], v105, v89, v[28:31]
	s_waitcnt lgkmcnt(5)
	v_mfma_f32_16x16x4_f32 v[28:31], v106, v90, v[28:31]
	s_waitcnt lgkmcnt(4)
	v_mfma_f32_16x16x4_f32 v[28:31], v107, v91, v[28:31]
	s_nop 9
	v_sub_f32_e32 v36, v32, v28
	v_sub_f32_e32 v37, v33, v29
	v_sub_f32_e32 v38, v34, v30
	v_sub_f32_e32 v39, v35, v31
	ds_write_b32 v9, v36 offset:12480
	ds_write_b32 v9, v37 offset:12740
	ds_write_b32 v9, v38 offset:13000
	ds_write_b32 v9, v39 offset:13260
	ds_read_b32 v40, v10 offset:12480
	ds_read_b32 v41, v10 offset:13520
	ds_read_b32 v42, v10 offset:14560
	ds_read_b32 v43, v10 offset:15600
	s_waitcnt lgkmcnt(11)
	s_waitcnt lgkmcnt(3)
	v_mfma_f32_16x16x4_f32 v[44:47], v108, v40, 0
	s_waitcnt lgkmcnt(2)
	v_mfma_f32_16x16x4_f32 v[44:47], v109, v41, v[44:47]
	s_waitcnt lgkmcnt(1)
	v_mfma_f32_16x16x4_f32 v[44:47], v110, v42, v[44:47]
	s_waitcnt lgkmcnt(0)
	v_mfma_f32_16x16x4_f32 v[44:47], v111, v43, v[44:47]
	s_nop 9
	ds_write_b32 v9, v44 offset:12480
	ds_write_b32 v9, v45 offset:12740
	ds_write_b32 v9, v46 offset:13000
	ds_write_b32 v9, v47 offset:13260
	s_waitcnt lgkmcnt(0)
